# FF1 K loops (P7,P15): LDS-DMA stage loads use SGPR base + 32-bit VGPR offset, no VALU address adds in the load segments
# speedup vs baseline: 1.0059x; 1.0059x over previous
; #define PG8_STAGE(bufoff, gbase, voff) do { _Pragma("unroll") for (int _i = 0; _i < 2; ++_i) \
;         __builtin_amdgcn_global_load_lds((const unsigned*)((const char*)(gbase) + (voff)[_i]), (PG8_LAS unsigned*)(lds + (bufoff) + ldsw + _i * 8192), 16, 0, 0); } while (0)
; #define PG8_LDA(dst, b, h) do { _Pragma("unroll") for (int m = 0; m < 4; ++m) _Pragma("unroll") for (int k = 0; k < 2; ++k) dst[m][k] = *(const PG8_LAS bf16x8*)(lds + PG8_SA(b, h) + aoff + m * 2048 + k * 1024); } while (0)
; #define PG8_LDB(dst, b, h) do { _Pragma("unroll") for (int n = 0; n < 2; ++n) _Pragma("unroll") for (int k = 0; k < 2; ++k) dst[n][k] = *(const PG8_LAS bf16x8*)(lds + PG8_SB(b, h) + boff + n * 2048 + k * 1024); } while (0)
; #define PG8_MMA(ai, bj, At, Bt) do { __builtin_amdgcn_s_setprio(1); _Pragma("unroll") for (int m = 0; m < 4; ++m) _Pragma("unroll") for (int n = 0; n < 2; ++n) _Pragma("unroll") for (int k = 0; k < 2; ++k) \
;         acc[ai][bj][m][n] = __builtin_amdgcn_mfma_f32_16x16x32_bf16(Bt[n][k], At[m][k], acc[ai][bj][m][n], 0, 0, 0); __builtin_amdgcn_s_setprio(0); } while (0)
; #define PG8_WAIT_V(n) asm volatile("s_waitcnt vmcnt(" #n ")" ::: "memory")
; #define PG8_WAIT_L(n) asm volatile("s_waitcnt lgkmcnt(" #n ")" ::: "memory")
; #define PG8_BAR __builtin_amdgcn_s_barrier()
; #define PG8_SCHED __builtin_amdgcn_sched_barrier(0)
; template <class Epi, class Sched, bool ALIGN_EPI = false, bool SP2 = false>
; __device__ __forceinline__ void gemm_phase(PG8_LAS unsigned char* lds, const Gemm g, const Sched& S, const Epi& E) {
;     ...
;             PG8_LDB(B0, 0, 0); PG8_LDB(B1, 0, 1); PG8_SCHED; PG8_LDA(At, 0, 0); PG8_STAGE(PG8_SA(1, 1), a1 + hstep, voffA);
;             PG8_WAIT_V(8); PG8_WAIT_L(0); PG8_BAR; PG8_MMA(0, 0, At, B0); PG8_MMA(0, 1, At, B1); PG8_BAR; PG8_SCHED;
;             PG8_LDA(At, 0, 1); PG8_STAGE(PG8_SB(0, 0), b2, voffB); PG8_STAGE(PG8_SB(0, 1), b2 + hstep, voffB); PG8_STAGE(PG8_SA(0, 0), a2, voffA);
;             PG8_WAIT_V(8); PG8_WAIT_L(0); PG8_BAR; PG8_MMA(1, 0, At, B0); PG8_MMA(1, 1, At, B1); PG8_BAR; PG8_SCHED;
.LBB0_714:
	ds_read_b128 v[154:157], v147
	ds_read_b128 v[158:161], v147 offset:1024
	ds_read_b128 v[162:165], v147 offset:2048
	ds_read_b128 v[166:169], v147 offset:3072
	ds_read_b128 v[170:173], v148
	ds_read_b128 v[174:177], v148 offset:1024
	ds_read_b128 v[178:181], v148 offset:2048
	ds_read_b128 v[182:185], v148 offset:3072
	s_add_u32 s33, s40, 0xfffc0080
	s_addc_u32 s34, s41, -1
	s_cmp_eq_u32 s76, 12
	s_cselect_b32 s45, s23, s34
	s_cselect_b32 s44, s72, s33
	s_cselect_b32 s43, s21, s75
	s_cselect_b32 s42, s73, s74
	s_add_i32 m0, s39, 0xc000
	ds_read_b128 v[186:189], v149
	ds_read_b128 v[190:193], v149 offset:1024
	ds_read_b128 v[194:197], v149 offset:2048
	ds_read_b128 v[198:201], v149 offset:3072
	ds_read_b128 v[202:205], v149 offset:4096
	ds_read_b128 v[206:209], v149 offset:5120
	ds_read_b128 v[210:213], v149 offset:6144
	ds_read_b128 v[214:217], v149 offset:7168
	global_load_lds_dwordx4 v136, s[40:41]
	s_add_i32 m0, s39, 0xe000
	s_nop 0
	global_load_lds_dwordx4 v138, s[40:41]
	s_waitcnt vmcnt(8)
	s_waitcnt lgkmcnt(0)
	s_barrier
	s_setprio 1
	s_waitcnt lgkmcnt(0)
	v_mfma_f32_16x16x32_bf16 v[124:127], v[154:157], v[186:189], v[124:127]
	v_mfma_f32_16x16x32_bf16 v[116:119], v[162:165], v[186:189], v[116:119]
	v_mfma_f32_16x16x32_bf16 v[108:111], v[154:157], v[194:197], v[108:111]
	v_mfma_f32_16x16x32_bf16 v[100:103], v[162:165], v[194:197], v[100:103]
	v_mfma_f32_16x16x32_bf16 v[92:95], v[154:157], v[202:205], v[92:95]
	v_mfma_f32_16x16x32_bf16 v[84:87], v[162:165], v[202:205], v[84:87]
	v_mfma_f32_16x16x32_bf16 v[76:79], v[154:157], v[210:213], v[76:79]
	v_mfma_f32_16x16x32_bf16 v[68:71], v[162:165], v[210:213], v[68:71]
	v_mfma_f32_16x16x32_bf16 v[124:127], v[158:161], v[190:193], v[124:127]
	v_mfma_f32_16x16x32_bf16 v[116:119], v[166:169], v[190:193], v[116:119]
	v_mfma_f32_16x16x32_bf16 v[108:111], v[158:161], v[198:201], v[108:111]
	v_mfma_f32_16x16x32_bf16 v[100:103], v[166:169], v[198:201], v[100:103]
	v_mfma_f32_16x16x32_bf16 v[92:95], v[158:161], v[206:209], v[92:95]
	v_mfma_f32_16x16x32_bf16 v[84:87], v[166:169], v[206:209], v[84:87]
	v_mfma_f32_16x16x32_bf16 v[76:79], v[158:161], v[214:217], v[76:79]
	v_mfma_f32_16x16x32_bf16 v[68:71], v[166:169], v[214:217], v[68:71]
	s_setprio 0
	s_setprio 1
	v_mfma_f32_16x16x32_bf16 v[120:123], v[170:173], v[186:189], v[120:123]
	v_mfma_f32_16x16x32_bf16 v[112:115], v[178:181], v[186:189], v[112:115]
	v_mfma_f32_16x16x32_bf16 v[104:107], v[170:173], v[194:197], v[104:107]
	v_mfma_f32_16x16x32_bf16 v[96:99], v[178:181], v[194:197], v[96:99]
	v_mfma_f32_16x16x32_bf16 v[88:91], v[170:173], v[202:205], v[88:91]
	v_mfma_f32_16x16x32_bf16 v[80:83], v[178:181], v[202:205], v[80:83]
	v_mfma_f32_16x16x32_bf16 v[72:75], v[170:173], v[210:213], v[72:75]
	v_mfma_f32_16x16x32_bf16 v[64:67], v[178:181], v[210:213], v[64:67]
	v_mfma_f32_16x16x32_bf16 v[120:123], v[174:177], v[190:193], v[120:123]
	v_mfma_f32_16x16x32_bf16 v[112:115], v[182:185], v[190:193], v[112:115]
	v_mfma_f32_16x16x32_bf16 v[104:107], v[174:177], v[198:201], v[104:107]
	v_mfma_f32_16x16x32_bf16 v[96:99], v[182:185], v[198:201], v[96:99]
	v_mfma_f32_16x16x32_bf16 v[88:91], v[174:177], v[206:209], v[88:91]
	v_mfma_f32_16x16x32_bf16 v[80:83], v[182:185], v[206:209], v[80:83]
	v_mfma_f32_16x16x32_bf16 v[72:75], v[174:177], v[214:217], v[72:75]
	v_mfma_f32_16x16x32_bf16 v[64:67], v[182:185], v[214:217], v[64:67]
	s_setprio 0
	s_barrier
	s_add_i32 s33, s62, s52
	s_add_u32 s82, s42, s10
	s_addc_u32 s83, s43, s11
	s_mov_b32 m0, s33
	ds_read_b128 v[186:189], v149 offset:16384
	ds_read_b128 v[190:193], v149 offset:17408
	ds_read_b128 v[194:197], v149 offset:18432
	ds_read_b128 v[198:201], v149 offset:19456
	ds_read_b128 v[202:205], v149 offset:20480
	ds_read_b128 v[206:209], v149 offset:21504
	ds_read_b128 v[210:213], v149 offset:22528
	ds_read_b128 v[214:217], v149 offset:23552
	global_load_lds_dwordx4 v130, s[42:43]
	s_add_i32 m0, s33, 0x2000
	s_add_u32 s78, s42, 0x40000
	s_addc_u32 s79, s43, 0
	s_add_i32 s33, s63, s52
	global_load_lds_dwordx4 v134, s[42:43]
	s_mov_b32 m0, s33
	s_add_u32 s84, s44, s10
	s_addc_u32 s85, s45, s11
	global_load_lds_dwordx4 v130, s[78:79]
	s_add_i32 m0, s33, 0x2000
	s_nop 0
	global_load_lds_dwordx4 v134, s[78:79]
	s_mov_b32 m0, s39
	s_nop 0
	global_load_lds_dwordx4 v128, s[44:45]
	s_mov_b32 m0, s55
	s_nop 0
	global_load_lds_dwordx4 v132, s[44:45]
	s_waitcnt vmcnt(8)
	s_waitcnt lgkmcnt(0)
	s_barrier
	s_setprio 1
	s_waitcnt lgkmcnt(0)
	v_mfma_f32_16x16x32_bf16 v[60:63], v[154:157], v[186:189], v[60:63]
	v_mfma_f32_16x16x32_bf16 v[52:55], v[162:165], v[186:189], v[52:55]
	v_mfma_f32_16x16x32_bf16 v[44:47], v[154:157], v[194:197], v[44:47]
	v_mfma_f32_16x16x32_bf16 v[36:39], v[162:165], v[194:197], v[36:39]
	v_mfma_f32_16x16x32_bf16 v[28:31], v[154:157], v[202:205], v[28:31]
	v_mfma_f32_16x16x32_bf16 v[20:23], v[162:165], v[202:205], v[20:23]
	v_mfma_f32_16x16x32_bf16 v[12:15], v[154:157], v[210:213], v[12:15]
	v_mfma_f32_16x16x32_bf16 v[4:7], v[162:165], v[210:213], v[4:7]
	v_mfma_f32_16x16x32_bf16 v[60:63], v[158:161], v[190:193], v[60:63]
	v_mfma_f32_16x16x32_bf16 v[52:55], v[166:169], v[190:193], v[52:55]
	v_mfma_f32_16x16x32_bf16 v[44:47], v[158:161], v[198:201], v[44:47]
	v_mfma_f32_16x16x32_bf16 v[36:39], v[166:169], v[198:201], v[36:39]
	v_mfma_f32_16x16x32_bf16 v[28:31], v[158:161], v[206:209], v[28:31]
	v_mfma_f32_16x16x32_bf16 v[20:23], v[166:169], v[206:209], v[20:23]
	v_mfma_f32_16x16x32_bf16 v[12:15], v[158:161], v[214:217], v[12:15]
	v_mfma_f32_16x16x32_bf16 v[4:7], v[166:169], v[214:217], v[4:7]
	s_setprio 0
	s_setprio 1
	v_mfma_f32_16x16x32_bf16 v[56:59], v[170:173], v[186:189], v[56:59]
	v_mfma_f32_16x16x32_bf16 v[48:51], v[178:181], v[186:189], v[48:51]
	v_mfma_f32_16x16x32_bf16 v[40:43], v[170:173], v[194:197], v[40:43]
	v_mfma_f32_16x16x32_bf16 v[32:35], v[178:181], v[194:197], v[32:35]
	v_mfma_f32_16x16x32_bf16 v[24:27], v[170:173], v[202:205], v[24:27]
	v_mfma_f32_16x16x32_bf16 v[16:19], v[178:181], v[202:205], v[16:19]
	v_mfma_f32_16x16x32_bf16 v[8:11], v[170:173], v[210:213], v[8:11]
	v_mfma_f32_16x16x32_bf16 v[0:3], v[178:181], v[210:213], v[0:3]
	v_mfma_f32_16x16x32_bf16 v[56:59], v[174:177], v[190:193], v[56:59]
	v_mfma_f32_16x16x32_bf16 v[48:51], v[182:185], v[190:193], v[48:51]
	v_mfma_f32_16x16x32_bf16 v[40:43], v[174:177], v[198:201], v[40:43]
	v_mfma_f32_16x16x32_bf16 v[32:35], v[182:185], v[198:201], v[32:35]
	v_mfma_f32_16x16x32_bf16 v[24:27], v[174:177], v[206:209], v[24:27]
	v_mfma_f32_16x16x32_bf16 v[16:19], v[182:185], v[206:209], v[16:19]
	v_mfma_f32_16x16x32_bf16 v[8:11], v[174:177], v[214:217], v[8:11]
	v_mfma_f32_16x16x32_bf16 v[0:3], v[182:185], v[214:217], v[0:3]
	s_setprio 0
	s_barrier
; #define PG8_STAGE(bufoff, gbase, voff) do { _Pragma("unroll") for (int _i = 0; _i < 2; ++_i) \
;         __builtin_amdgcn_global_load_lds((const unsigned*)((const char*)(gbase) + (voff)[_i]), (PG8_LAS unsigned*)(lds + (bufoff) + ldsw + _i * 8192), 16, 0, 0); } while (0)
; #define PG8_LDA(dst, b, h) do { _Pragma("unroll") for (int m = 0; m < 4; ++m) _Pragma("unroll") for (int k = 0; k < 2; ++k) dst[m][k] = *(const PG8_LAS bf16x8*)(lds + PG8_SA(b, h) + aoff + m * 2048 + k * 1024); } while (0)
; #define PG8_LDB(dst, b, h) do { _Pragma("unroll") for (int n = 0; n < 2; ++n) _Pragma("unroll") for (int k = 0; k < 2; ++k) dst[n][k] = *(const PG8_LAS bf16x8*)(lds + PG8_SB(b, h) + boff + n * 2048 + k * 1024); } while (0)
; #define PG8_MMA(ai, bj, At, Bt) do { __builtin_amdgcn_s_setprio(1); _Pragma("unroll") for (int m = 0; m < 4; ++m) _Pragma("unroll") for (int n = 0; n < 2; ++n) _Pragma("unroll") for (int k = 0; k < 2; ++k) \
;         acc[ai][bj][m][n] = __builtin_amdgcn_mfma_f32_16x16x32_bf16(Bt[n][k], At[m][k], acc[ai][bj][m][n], 0, 0, 0); __builtin_amdgcn_s_setprio(0); } while (0)
; #define PG8_WAIT_V(n) asm volatile("s_waitcnt vmcnt(" #n ")" ::: "memory")
; #define PG8_WAIT_L(n) asm volatile("s_waitcnt lgkmcnt(" #n ")" ::: "memory")
; #define PG8_BAR __builtin_amdgcn_s_barrier()
; #define PG8_SCHED __builtin_amdgcn_sched_barrier(0)
; template <class Epi, class Sched, bool ALIGN_EPI = false, bool SP2 = false>
; __device__ __forceinline__ void gemm_phase(PG8_LAS unsigned char* lds, const Gemm g, const Sched& S, const Epi& E) {
;     ...
;         for (int t = 0; t < nt; t += 2) {
;     ...
;             PG8_LDB(B0, 1, 0); PG8_LDB(B1, 1, 1); PG8_SCHED; PG8_LDA(At, 1, 0); PG8_STAGE(PG8_SA(0, 1), a2 + hstep, voffA);
;             PG8_WAIT_V(8); PG8_WAIT_L(0); PG8_BAR; PG8_MMA(0, 0, At, B0); PG8_MMA(0, 1, At, B1); PG8_BAR; PG8_SCHED;
;             PG8_LDA(At, 1, 1); PG8_STAGE(PG8_SB(1, 0), b3, voffB); PG8_STAGE(PG8_SB(1, 1), b3 + hstep, voffB); PG8_STAGE(PG8_SA(1, 0), a3, voffA);
;             PG8_WAIT_V(8); PG8_WAIT_L(0); PG8_BAR; PG8_MMA(1, 0, At, B0); PG8_MMA(1, 1, At, B1); PG8_BAR; PG8_SCHED;
	s_add_i32 s33, 0, 0x18000
	v_add_u32_e32 v153, s33, v145
	s_add_i32 s34, 0, 0x1c000
	ds_read_b128 v[154:157], v153
	ds_read_b128 v[158:161], v153 offset:1024
	ds_read_b128 v[162:165], v153 offset:2048
	ds_read_b128 v[166:169], v153 offset:3072
	v_add_u32_e32 v153, s34, v145
	ds_read_b128 v[170:173], v153
	ds_read_b128 v[174:177], v153 offset:1024
	ds_read_b128 v[178:181], v153 offset:2048
	ds_read_b128 v[182:185], v153 offset:3072
	s_add_u32 s44, s44, 0x40000
	s_addc_u32 s45, s45, 0
	s_mov_b32 m0, s56
	ds_read_b128 v[186:189], v149 offset:32768
	ds_read_b128 v[190:193], v149 offset:33792
	ds_read_b128 v[194:197], v149 offset:34816
	ds_read_b128 v[198:201], v149 offset:35840
	ds_read_b128 v[202:205], v149 offset:36864
	ds_read_b128 v[206:209], v149 offset:37888
	ds_read_b128 v[210:213], v149 offset:38912
	ds_read_b128 v[214:217], v149 offset:39936
	global_load_lds_dwordx4 v128, s[44:45]
	s_mov_b32 m0, s57
	s_nop 0
	global_load_lds_dwordx4 v132, s[44:45]
	s_waitcnt vmcnt(8)
	s_waitcnt lgkmcnt(0)
	s_barrier
	s_setprio 1
	s_waitcnt lgkmcnt(0)
	v_mfma_f32_16x16x32_bf16 v[124:127], v[154:157], v[186:189], v[124:127]
	v_mfma_f32_16x16x32_bf16 v[116:119], v[162:165], v[186:189], v[116:119]
	v_mfma_f32_16x16x32_bf16 v[108:111], v[154:157], v[194:197], v[108:111]
	v_mfma_f32_16x16x32_bf16 v[100:103], v[162:165], v[194:197], v[100:103]
	v_mfma_f32_16x16x32_bf16 v[92:95], v[154:157], v[202:205], v[92:95]
	v_mfma_f32_16x16x32_bf16 v[84:87], v[162:165], v[202:205], v[84:87]
	v_mfma_f32_16x16x32_bf16 v[76:79], v[154:157], v[210:213], v[76:79]
	v_mfma_f32_16x16x32_bf16 v[68:71], v[162:165], v[210:213], v[68:71]
	v_mfma_f32_16x16x32_bf16 v[124:127], v[158:161], v[190:193], v[124:127]
	v_mfma_f32_16x16x32_bf16 v[116:119], v[166:169], v[190:193], v[116:119]
	v_mfma_f32_16x16x32_bf16 v[108:111], v[158:161], v[198:201], v[108:111]
	v_mfma_f32_16x16x32_bf16 v[100:103], v[166:169], v[198:201], v[100:103]
	v_mfma_f32_16x16x32_bf16 v[92:95], v[158:161], v[206:209], v[92:95]
	v_mfma_f32_16x16x32_bf16 v[84:87], v[166:169], v[206:209], v[84:87]
	v_mfma_f32_16x16x32_bf16 v[76:79], v[158:161], v[214:217], v[76:79]
	v_mfma_f32_16x16x32_bf16 v[68:71], v[166:169], v[214:217], v[68:71]
	s_setprio 0
	s_setprio 1
	v_mfma_f32_16x16x32_bf16 v[120:123], v[170:173], v[186:189], v[120:123]
	v_mfma_f32_16x16x32_bf16 v[112:115], v[178:181], v[186:189], v[112:115]
	v_mfma_f32_16x16x32_bf16 v[104:107], v[170:173], v[194:197], v[104:107]
	v_mfma_f32_16x16x32_bf16 v[96:99], v[178:181], v[194:197], v[96:99]
	v_mfma_f32_16x16x32_bf16 v[88:91], v[170:173], v[202:205], v[88:91]
	v_mfma_f32_16x16x32_bf16 v[80:83], v[178:181], v[202:205], v[80:83]
	v_mfma_f32_16x16x32_bf16 v[72:75], v[170:173], v[210:213], v[72:75]
	v_mfma_f32_16x16x32_bf16 v[64:67], v[178:181], v[210:213], v[64:67]
	v_mfma_f32_16x16x32_bf16 v[120:123], v[174:177], v[190:193], v[120:123]
	v_mfma_f32_16x16x32_bf16 v[112:115], v[182:185], v[190:193], v[112:115]
	v_mfma_f32_16x16x32_bf16 v[104:107], v[174:177], v[198:201], v[104:107]
	v_mfma_f32_16x16x32_bf16 v[96:99], v[182:185], v[198:201], v[96:99]
	v_mfma_f32_16x16x32_bf16 v[88:91], v[174:177], v[206:209], v[88:91]
	v_mfma_f32_16x16x32_bf16 v[80:83], v[182:185], v[206:209], v[80:83]
	v_mfma_f32_16x16x32_bf16 v[72:75], v[174:177], v[214:217], v[72:75]
	v_mfma_f32_16x16x32_bf16 v[64:67], v[182:185], v[214:217], v[64:67]
	s_setprio 0
	s_barrier
	s_add_i32 s33, s33, s52
	s_mov_b32 m0, s33
	ds_read_b128 v[186:189], v149 offset:49152
	ds_read_b128 v[190:193], v149 offset:50176
	ds_read_b128 v[194:197], v149 offset:51200
	ds_read_b128 v[198:201], v149 offset:52224
	ds_read_b128 v[202:205], v149 offset:53248
	ds_read_b128 v[206:209], v149 offset:54272
	ds_read_b128 v[210:213], v149 offset:55296
	ds_read_b128 v[214:217], v149 offset:56320
	global_load_lds_dwordx4 v130, s[82:83]
	s_add_i32 m0, s33, 0x2000
	s_add_u32 s42, s42, 0x40080
	s_addc_u32 s43, s43, 0
	s_add_i32 s33, s34, s52
	global_load_lds_dwordx4 v134, s[82:83]
	s_mov_b32 m0, s33
	s_nop 0
	global_load_lds_dwordx4 v130, s[42:43]
	s_add_i32 m0, s33, 0x2000
	s_nop 0
	global_load_lds_dwordx4 v134, s[42:43]
	s_mov_b32 m0, s60
	s_nop 0
	global_load_lds_dwordx4 v128, s[84:85]
	s_mov_b32 m0, s61
	s_nop 0
	global_load_lds_dwordx4 v132, s[84:85]
	s_waitcnt vmcnt(8)
	s_waitcnt lgkmcnt(0)
	s_barrier
	s_setprio 1
	s_waitcnt lgkmcnt(0)
	v_mfma_f32_16x16x32_bf16 v[60:63], v[154:157], v[186:189], v[60:63]
	v_mfma_f32_16x16x32_bf16 v[52:55], v[162:165], v[186:189], v[52:55]
	v_mfma_f32_16x16x32_bf16 v[44:47], v[154:157], v[194:197], v[44:47]
	v_mfma_f32_16x16x32_bf16 v[36:39], v[162:165], v[194:197], v[36:39]
	v_mfma_f32_16x16x32_bf16 v[28:31], v[154:157], v[202:205], v[28:31]
	v_mfma_f32_16x16x32_bf16 v[20:23], v[162:165], v[202:205], v[20:23]
	v_mfma_f32_16x16x32_bf16 v[12:15], v[154:157], v[210:213], v[12:15]
	v_mfma_f32_16x16x32_bf16 v[4:7], v[162:165], v[210:213], v[4:7]
	v_mfma_f32_16x16x32_bf16 v[60:63], v[158:161], v[190:193], v[60:63]
	v_mfma_f32_16x16x32_bf16 v[52:55], v[166:169], v[190:193], v[52:55]
	v_mfma_f32_16x16x32_bf16 v[44:47], v[158:161], v[198:201], v[44:47]
	v_mfma_f32_16x16x32_bf16 v[36:39], v[166:169], v[198:201], v[36:39]
	v_mfma_f32_16x16x32_bf16 v[28:31], v[158:161], v[206:209], v[28:31]
	v_mfma_f32_16x16x32_bf16 v[20:23], v[166:169], v[206:209], v[20:23]
	v_mfma_f32_16x16x32_bf16 v[12:15], v[158:161], v[214:217], v[12:15]
	v_mfma_f32_16x16x32_bf16 v[4:7], v[166:169], v[214:217], v[4:7]
	s_setprio 0
	s_setprio 1
	v_mfma_f32_16x16x32_bf16 v[56:59], v[170:173], v[186:189], v[56:59]
	v_mfma_f32_16x16x32_bf16 v[48:51], v[178:181], v[186:189], v[48:51]
	v_mfma_f32_16x16x32_bf16 v[40:43], v[170:173], v[194:197], v[40:43]
	v_mfma_f32_16x16x32_bf16 v[32:35], v[178:181], v[194:197], v[32:35]
	v_mfma_f32_16x16x32_bf16 v[24:27], v[170:173], v[202:205], v[24:27]
	v_mfma_f32_16x16x32_bf16 v[16:19], v[178:181], v[202:205], v[16:19]
	v_mfma_f32_16x16x32_bf16 v[8:11], v[170:173], v[210:213], v[8:11]
	v_mfma_f32_16x16x32_bf16 v[0:3], v[178:181], v[210:213], v[0:3]
	v_mfma_f32_16x16x32_bf16 v[56:59], v[174:177], v[190:193], v[56:59]
	v_mfma_f32_16x16x32_bf16 v[48:51], v[182:185], v[190:193], v[48:51]
	v_mfma_f32_16x16x32_bf16 v[40:43], v[174:177], v[198:201], v[40:43]
	v_mfma_f32_16x16x32_bf16 v[32:35], v[182:185], v[198:201], v[32:35]
	v_mfma_f32_16x16x32_bf16 v[24:27], v[174:177], v[206:209], v[24:27]
	v_mfma_f32_16x16x32_bf16 v[16:19], v[182:185], v[206:209], v[16:19]
	v_mfma_f32_16x16x32_bf16 v[8:11], v[174:177], v[214:217], v[8:11]
	v_mfma_f32_16x16x32_bf16 v[0:3], v[182:185], v[214:217], v[0:3]
	s_setprio 0
	s_barrier
	s_add_i32 s76, s76, 2
	s_add_u32 s40, s40, 0x100
	s_addc_u32 s41, s41, 0
	s_add_u32 s74, s74, 0x100
	s_addc_u32 s75, s75, 0
	s_cmp_gt_u32 s76, 13
	s_cbranch_scc0 .LBB0_714
	s_and_b64 vcc, exec, s[12:13]
	s_cbranch_vccz .LBB0_717
	s_barrier

; #define PG8_STAGE(bufoff, gbase, voff) do { _Pragma("unroll") for (int _i = 0; _i < 2; ++_i) \
;         __builtin_amdgcn_global_load_lds((const unsigned*)((const char*)(gbase) + (voff)[_i]), (PG8_LAS unsigned*)(lds + (bufoff) + ldsw + _i * 8192), 16, 0, 0); } while (0)
; #define PG8_LDA(dst, b, h) do { _Pragma("unroll") for (int m = 0; m < 4; ++m) _Pragma("unroll") for (int k = 0; k < 2; ++k) dst[m][k] = *(const PG8_LAS bf16x8*)(lds + PG8_SA(b, h) + aoff + m * 2048 + k * 1024); } while (0)
; #define PG8_LDB(dst, b, h) do { _Pragma("unroll") for (int n = 0; n < 2; ++n) _Pragma("unroll") for (int k = 0; k < 2; ++k) dst[n][k] = *(const PG8_LAS bf16x8*)(lds + PG8_SB(b, h) + boff + n * 2048 + k * 1024); } while (0)
; #define PG8_MMA(ai, bj, At, Bt) do { __builtin_amdgcn_s_setprio(1); _Pragma("unroll") for (int m = 0; m < 4; ++m) _Pragma("unroll") for (int n = 0; n < 2; ++n) _Pragma("unroll") for (int k = 0; k < 2; ++k) \
;         acc[ai][bj][m][n] = __builtin_amdgcn_mfma_f32_16x16x32_bf16(Bt[n][k], At[m][k], acc[ai][bj][m][n], 0, 0, 0); __builtin_amdgcn_s_setprio(0); } while (0)
; #define PG8_WAIT_V(n) asm volatile("s_waitcnt vmcnt(" #n ")" ::: "memory")
; #define PG8_WAIT_L(n) asm volatile("s_waitcnt lgkmcnt(" #n ")" ::: "memory")
; #define PG8_BAR __builtin_amdgcn_s_barrier()
; #define PG8_SCHED __builtin_amdgcn_sched_barrier(0)
; template <class Epi, class Sched, bool ALIGN_EPI = false, bool SP2 = false>
; __device__ __forceinline__ void gemm_phase(PG8_LAS unsigned char* lds, const Gemm g, const Sched& S, const Epi& E) {
;     ...
;             PG8_LDB(B0, 0, 0); PG8_LDB(B1, 0, 1); PG8_SCHED; PG8_LDA(At, 0, 0); PG8_STAGE(PG8_SA(1, 1), a1 + hstep, voffA);
;             PG8_WAIT_V(8); PG8_WAIT_L(0); PG8_BAR; PG8_MMA(0, 0, At, B0); PG8_MMA(0, 1, At, B1); PG8_BAR; PG8_SCHED;
;             PG8_LDA(At, 0, 1); PG8_STAGE(PG8_SB(0, 0), b2, voffB); PG8_STAGE(PG8_SB(0, 1), b2 + hstep, voffB); PG8_STAGE(PG8_SA(0, 0), a2, voffA);
;             PG8_WAIT_V(8); PG8_WAIT_L(0); PG8_BAR; PG8_MMA(1, 0, At, B0); PG8_MMA(1, 1, At, B1); PG8_BAR; PG8_SCHED;
.LBB0_1342:
	ds_read_b128 v[154:157], v147
	ds_read_b128 v[158:161], v147 offset:1024
	ds_read_b128 v[162:165], v147 offset:2048
	ds_read_b128 v[166:169], v147 offset:3072
	ds_read_b128 v[170:173], v148
	ds_read_b128 v[174:177], v148 offset:1024
	ds_read_b128 v[178:181], v148 offset:2048
	ds_read_b128 v[182:185], v148 offset:3072
	s_add_u32 s33, s36, 0xfffc0080
	s_addc_u32 s34, s37, -1
	s_cmp_eq_u32 s62, 12
	s_cselect_b32 s41, s19, s34
	s_cselect_b32 s40, s58, s33
	s_cselect_b32 s39, s15, s61
	s_cselect_b32 s38, s59, s60
	s_add_i32 m0, s25, 0xc000
	ds_read_b128 v[186:189], v149
	ds_read_b128 v[190:193], v149 offset:1024
	ds_read_b128 v[194:197], v149 offset:2048
	ds_read_b128 v[198:201], v149 offset:3072
	ds_read_b128 v[202:205], v149 offset:4096
	ds_read_b128 v[206:209], v149 offset:5120
	ds_read_b128 v[210:213], v149 offset:6144
	ds_read_b128 v[214:217], v149 offset:7168
	global_load_lds_dwordx4 v136, s[36:37]
	s_add_i32 m0, s25, 0xe000
	s_nop 0
	global_load_lds_dwordx4 v138, s[36:37]
	s_waitcnt vmcnt(8)
	s_waitcnt lgkmcnt(0)
	s_barrier
	s_setprio 1
	s_waitcnt lgkmcnt(0)
	v_mfma_f32_16x16x32_bf16 v[124:127], v[154:157], v[186:189], v[124:127]
	v_mfma_f32_16x16x32_bf16 v[116:119], v[162:165], v[186:189], v[116:119]
	v_mfma_f32_16x16x32_bf16 v[108:111], v[154:157], v[194:197], v[108:111]
	v_mfma_f32_16x16x32_bf16 v[100:103], v[162:165], v[194:197], v[100:103]
	v_mfma_f32_16x16x32_bf16 v[92:95], v[154:157], v[202:205], v[92:95]
	v_mfma_f32_16x16x32_bf16 v[84:87], v[162:165], v[202:205], v[84:87]
	v_mfma_f32_16x16x32_bf16 v[76:79], v[154:157], v[210:213], v[76:79]
	v_mfma_f32_16x16x32_bf16 v[68:71], v[162:165], v[210:213], v[68:71]
	v_mfma_f32_16x16x32_bf16 v[124:127], v[158:161], v[190:193], v[124:127]
	v_mfma_f32_16x16x32_bf16 v[116:119], v[166:169], v[190:193], v[116:119]
	v_mfma_f32_16x16x32_bf16 v[108:111], v[158:161], v[198:201], v[108:111]
	v_mfma_f32_16x16x32_bf16 v[100:103], v[166:169], v[198:201], v[100:103]
	v_mfma_f32_16x16x32_bf16 v[92:95], v[158:161], v[206:209], v[92:95]
	v_mfma_f32_16x16x32_bf16 v[84:87], v[166:169], v[206:209], v[84:87]
	v_mfma_f32_16x16x32_bf16 v[76:79], v[158:161], v[214:217], v[76:79]
	v_mfma_f32_16x16x32_bf16 v[68:71], v[166:169], v[214:217], v[68:71]
	s_setprio 0
	s_setprio 1
	v_mfma_f32_16x16x32_bf16 v[120:123], v[170:173], v[186:189], v[120:123]
	v_mfma_f32_16x16x32_bf16 v[112:115], v[178:181], v[186:189], v[112:115]
	v_mfma_f32_16x16x32_bf16 v[104:107], v[170:173], v[194:197], v[104:107]
	v_mfma_f32_16x16x32_bf16 v[96:99], v[178:181], v[194:197], v[96:99]
	v_mfma_f32_16x16x32_bf16 v[88:91], v[170:173], v[202:205], v[88:91]
	v_mfma_f32_16x16x32_bf16 v[80:83], v[178:181], v[202:205], v[80:83]
	v_mfma_f32_16x16x32_bf16 v[72:75], v[170:173], v[210:213], v[72:75]
	v_mfma_f32_16x16x32_bf16 v[64:67], v[178:181], v[210:213], v[64:67]
	v_mfma_f32_16x16x32_bf16 v[120:123], v[174:177], v[190:193], v[120:123]
	v_mfma_f32_16x16x32_bf16 v[112:115], v[182:185], v[190:193], v[112:115]
	v_mfma_f32_16x16x32_bf16 v[104:107], v[174:177], v[198:201], v[104:107]
	v_mfma_f32_16x16x32_bf16 v[96:99], v[182:185], v[198:201], v[96:99]
	v_mfma_f32_16x16x32_bf16 v[88:91], v[174:177], v[206:209], v[88:91]
	v_mfma_f32_16x16x32_bf16 v[80:83], v[182:185], v[206:209], v[80:83]
	v_mfma_f32_16x16x32_bf16 v[72:75], v[174:177], v[214:217], v[72:75]
	v_mfma_f32_16x16x32_bf16 v[64:67], v[182:185], v[214:217], v[64:67]
	s_setprio 0
	s_barrier
	s_add_i32 s33, s54, s44
	s_add_u32 s82, s38, s10
	s_addc_u32 s83, s39, s11
	s_mov_b32 m0, s33
	ds_read_b128 v[186:189], v149 offset:16384
	ds_read_b128 v[190:193], v149 offset:17408
	ds_read_b128 v[194:197], v149 offset:18432
	ds_read_b128 v[198:201], v149 offset:19456
	ds_read_b128 v[202:205], v149 offset:20480
	ds_read_b128 v[206:209], v149 offset:21504
	ds_read_b128 v[210:213], v149 offset:22528
	ds_read_b128 v[214:217], v149 offset:23552
	global_load_lds_dwordx4 v130, s[38:39]
	s_add_i32 m0, s33, 0x2000
	s_add_u32 s64, s38, 0x40000
	s_addc_u32 s65, s39, 0
	s_add_i32 s33, s55, s44
	global_load_lds_dwordx4 v134, s[38:39]
	s_mov_b32 m0, s33
	s_add_u32 s84, s40, s10
	s_addc_u32 s85, s41, s11
	global_load_lds_dwordx4 v130, s[64:65]
	s_add_i32 m0, s33, 0x2000
	s_nop 0
	global_load_lds_dwordx4 v134, s[64:65]
	s_mov_b32 m0, s25
	s_nop 0
	global_load_lds_dwordx4 v128, s[40:41]
	s_mov_b32 m0, s47
	s_nop 0
	global_load_lds_dwordx4 v132, s[40:41]
	s_waitcnt vmcnt(8)
	s_waitcnt lgkmcnt(0)
	s_barrier
	s_setprio 1
	s_waitcnt lgkmcnt(0)
	v_mfma_f32_16x16x32_bf16 v[60:63], v[154:157], v[186:189], v[60:63]
	v_mfma_f32_16x16x32_bf16 v[52:55], v[162:165], v[186:189], v[52:55]
	v_mfma_f32_16x16x32_bf16 v[44:47], v[154:157], v[194:197], v[44:47]
	v_mfma_f32_16x16x32_bf16 v[36:39], v[162:165], v[194:197], v[36:39]
	v_mfma_f32_16x16x32_bf16 v[28:31], v[154:157], v[202:205], v[28:31]
	v_mfma_f32_16x16x32_bf16 v[20:23], v[162:165], v[202:205], v[20:23]
	v_mfma_f32_16x16x32_bf16 v[12:15], v[154:157], v[210:213], v[12:15]
	v_mfma_f32_16x16x32_bf16 v[4:7], v[162:165], v[210:213], v[4:7]
	v_mfma_f32_16x16x32_bf16 v[60:63], v[158:161], v[190:193], v[60:63]
	v_mfma_f32_16x16x32_bf16 v[52:55], v[166:169], v[190:193], v[52:55]
	v_mfma_f32_16x16x32_bf16 v[44:47], v[158:161], v[198:201], v[44:47]
	v_mfma_f32_16x16x32_bf16 v[36:39], v[166:169], v[198:201], v[36:39]
	v_mfma_f32_16x16x32_bf16 v[28:31], v[158:161], v[206:209], v[28:31]
	v_mfma_f32_16x16x32_bf16 v[20:23], v[166:169], v[206:209], v[20:23]
	v_mfma_f32_16x16x32_bf16 v[12:15], v[158:161], v[214:217], v[12:15]
	v_mfma_f32_16x16x32_bf16 v[4:7], v[166:169], v[214:217], v[4:7]
	s_setprio 0
	s_setprio 1
	v_mfma_f32_16x16x32_bf16 v[56:59], v[170:173], v[186:189], v[56:59]
	v_mfma_f32_16x16x32_bf16 v[48:51], v[178:181], v[186:189], v[48:51]
	v_mfma_f32_16x16x32_bf16 v[40:43], v[170:173], v[194:197], v[40:43]
	v_mfma_f32_16x16x32_bf16 v[32:35], v[178:181], v[194:197], v[32:35]
	v_mfma_f32_16x16x32_bf16 v[24:27], v[170:173], v[202:205], v[24:27]
	v_mfma_f32_16x16x32_bf16 v[16:19], v[178:181], v[202:205], v[16:19]
	v_mfma_f32_16x16x32_bf16 v[8:11], v[170:173], v[210:213], v[8:11]
	v_mfma_f32_16x16x32_bf16 v[0:3], v[178:181], v[210:213], v[0:3]
	v_mfma_f32_16x16x32_bf16 v[56:59], v[174:177], v[190:193], v[56:59]
	v_mfma_f32_16x16x32_bf16 v[48:51], v[182:185], v[190:193], v[48:51]
	v_mfma_f32_16x16x32_bf16 v[40:43], v[174:177], v[198:201], v[40:43]
	v_mfma_f32_16x16x32_bf16 v[32:35], v[182:185], v[198:201], v[32:35]
	v_mfma_f32_16x16x32_bf16 v[24:27], v[174:177], v[206:209], v[24:27]
	v_mfma_f32_16x16x32_bf16 v[16:19], v[182:185], v[206:209], v[16:19]
	v_mfma_f32_16x16x32_bf16 v[8:11], v[174:177], v[214:217], v[8:11]
	v_mfma_f32_16x16x32_bf16 v[0:3], v[182:185], v[214:217], v[0:3]
	s_setprio 0
	s_barrier
; #define PG8_STAGE(bufoff, gbase, voff) do { _Pragma("unroll") for (int _i = 0; _i < 2; ++_i) \
;         __builtin_amdgcn_global_load_lds((const unsigned*)((const char*)(gbase) + (voff)[_i]), (PG8_LAS unsigned*)(lds + (bufoff) + ldsw + _i * 8192), 16, 0, 0); } while (0)
; #define PG8_LDA(dst, b, h) do { _Pragma("unroll") for (int m = 0; m < 4; ++m) _Pragma("unroll") for (int k = 0; k < 2; ++k) dst[m][k] = *(const PG8_LAS bf16x8*)(lds + PG8_SA(b, h) + aoff + m * 2048 + k * 1024); } while (0)
; #define PG8_LDB(dst, b, h) do { _Pragma("unroll") for (int n = 0; n < 2; ++n) _Pragma("unroll") for (int k = 0; k < 2; ++k) dst[n][k] = *(const PG8_LAS bf16x8*)(lds + PG8_SB(b, h) + boff + n * 2048 + k * 1024); } while (0)
; #define PG8_MMA(ai, bj, At, Bt) do { __builtin_amdgcn_s_setprio(1); _Pragma("unroll") for (int m = 0; m < 4; ++m) _Pragma("unroll") for (int n = 0; n < 2; ++n) _Pragma("unroll") for (int k = 0; k < 2; ++k) \
;         acc[ai][bj][m][n] = __builtin_amdgcn_mfma_f32_16x16x32_bf16(Bt[n][k], At[m][k], acc[ai][bj][m][n], 0, 0, 0); __builtin_amdgcn_s_setprio(0); } while (0)
; #define PG8_WAIT_V(n) asm volatile("s_waitcnt vmcnt(" #n ")" ::: "memory")
; #define PG8_WAIT_L(n) asm volatile("s_waitcnt lgkmcnt(" #n ")" ::: "memory")
; #define PG8_BAR __builtin_amdgcn_s_barrier()
; #define PG8_SCHED __builtin_amdgcn_sched_barrier(0)
; template <class Epi, class Sched, bool ALIGN_EPI = false, bool SP2 = false>
; __device__ __forceinline__ void gemm_phase(PG8_LAS unsigned char* lds, const Gemm g, const Sched& S, const Epi& E) {
;     ...
;         for (int t = 0; t < nt; t += 2) {
;     ...
;             PG8_LDB(B0, 1, 0); PG8_LDB(B1, 1, 1); PG8_SCHED; PG8_LDA(At, 1, 0); PG8_STAGE(PG8_SA(0, 1), a2 + hstep, voffA);
;             PG8_WAIT_V(8); PG8_WAIT_L(0); PG8_BAR; PG8_MMA(0, 0, At, B0); PG8_MMA(0, 1, At, B1); PG8_BAR; PG8_SCHED;
;             PG8_LDA(At, 1, 1); PG8_STAGE(PG8_SB(1, 0), b3, voffB); PG8_STAGE(PG8_SB(1, 1), b3 + hstep, voffB); PG8_STAGE(PG8_SA(1, 0), a3, voffA);
;             PG8_WAIT_V(8); PG8_WAIT_L(0); PG8_BAR; PG8_MMA(1, 0, At, B0); PG8_MMA(1, 1, At, B1); PG8_BAR; PG8_SCHED;
	s_add_i32 s33, 0, 0x18000
	v_add_u32_e32 v153, s33, v145
	s_add_i32 s34, 0, 0x1c000
	ds_read_b128 v[154:157], v153
	ds_read_b128 v[158:161], v153 offset:1024
	ds_read_b128 v[162:165], v153 offset:2048
	ds_read_b128 v[166:169], v153 offset:3072
	v_add_u32_e32 v153, s34, v145
	ds_read_b128 v[170:173], v153
	ds_read_b128 v[174:177], v153 offset:1024
	ds_read_b128 v[178:181], v153 offset:2048
	ds_read_b128 v[182:185], v153 offset:3072
	s_add_u32 s40, s40, 0x40000
	s_addc_u32 s41, s41, 0
	s_mov_b32 m0, s48
	ds_read_b128 v[186:189], v149 offset:32768
	ds_read_b128 v[190:193], v149 offset:33792
	ds_read_b128 v[194:197], v149 offset:34816
	ds_read_b128 v[198:201], v149 offset:35840
	ds_read_b128 v[202:205], v149 offset:36864
	ds_read_b128 v[206:209], v149 offset:37888
	ds_read_b128 v[210:213], v149 offset:38912
	ds_read_b128 v[214:217], v149 offset:39936
	global_load_lds_dwordx4 v128, s[40:41]
	s_mov_b32 m0, s49
	s_nop 0
	global_load_lds_dwordx4 v132, s[40:41]
	s_waitcnt vmcnt(8)
	s_waitcnt lgkmcnt(0)
	s_barrier
	s_setprio 1
	s_waitcnt lgkmcnt(0)
	v_mfma_f32_16x16x32_bf16 v[124:127], v[154:157], v[186:189], v[124:127]
	v_mfma_f32_16x16x32_bf16 v[116:119], v[162:165], v[186:189], v[116:119]
	v_mfma_f32_16x16x32_bf16 v[108:111], v[154:157], v[194:197], v[108:111]
	v_mfma_f32_16x16x32_bf16 v[100:103], v[162:165], v[194:197], v[100:103]
	v_mfma_f32_16x16x32_bf16 v[92:95], v[154:157], v[202:205], v[92:95]
	v_mfma_f32_16x16x32_bf16 v[84:87], v[162:165], v[202:205], v[84:87]
	v_mfma_f32_16x16x32_bf16 v[76:79], v[154:157], v[210:213], v[76:79]
	v_mfma_f32_16x16x32_bf16 v[68:71], v[162:165], v[210:213], v[68:71]
	v_mfma_f32_16x16x32_bf16 v[124:127], v[158:161], v[190:193], v[124:127]
	v_mfma_f32_16x16x32_bf16 v[116:119], v[166:169], v[190:193], v[116:119]
	v_mfma_f32_16x16x32_bf16 v[108:111], v[158:161], v[198:201], v[108:111]
	v_mfma_f32_16x16x32_bf16 v[100:103], v[166:169], v[198:201], v[100:103]
	v_mfma_f32_16x16x32_bf16 v[92:95], v[158:161], v[206:209], v[92:95]
	v_mfma_f32_16x16x32_bf16 v[84:87], v[166:169], v[206:209], v[84:87]
	v_mfma_f32_16x16x32_bf16 v[76:79], v[158:161], v[214:217], v[76:79]
	v_mfma_f32_16x16x32_bf16 v[68:71], v[166:169], v[214:217], v[68:71]
	s_setprio 0
	s_setprio 1
	v_mfma_f32_16x16x32_bf16 v[120:123], v[170:173], v[186:189], v[120:123]
	v_mfma_f32_16x16x32_bf16 v[112:115], v[178:181], v[186:189], v[112:115]
	v_mfma_f32_16x16x32_bf16 v[104:107], v[170:173], v[194:197], v[104:107]
	v_mfma_f32_16x16x32_bf16 v[96:99], v[178:181], v[194:197], v[96:99]
	v_mfma_f32_16x16x32_bf16 v[88:91], v[170:173], v[202:205], v[88:91]
	v_mfma_f32_16x16x32_bf16 v[80:83], v[178:181], v[202:205], v[80:83]
	v_mfma_f32_16x16x32_bf16 v[72:75], v[170:173], v[210:213], v[72:75]
	v_mfma_f32_16x16x32_bf16 v[64:67], v[178:181], v[210:213], v[64:67]
	v_mfma_f32_16x16x32_bf16 v[120:123], v[174:177], v[190:193], v[120:123]
	v_mfma_f32_16x16x32_bf16 v[112:115], v[182:185], v[190:193], v[112:115]
	v_mfma_f32_16x16x32_bf16 v[104:107], v[174:177], v[198:201], v[104:107]
	v_mfma_f32_16x16x32_bf16 v[96:99], v[182:185], v[198:201], v[96:99]
	v_mfma_f32_16x16x32_bf16 v[88:91], v[174:177], v[206:209], v[88:91]
	v_mfma_f32_16x16x32_bf16 v[80:83], v[182:185], v[206:209], v[80:83]
	v_mfma_f32_16x16x32_bf16 v[72:75], v[174:177], v[214:217], v[72:75]
	v_mfma_f32_16x16x32_bf16 v[64:67], v[182:185], v[214:217], v[64:67]
	s_setprio 0
	s_barrier
	s_add_i32 s33, s33, s44
	s_mov_b32 m0, s33
	ds_read_b128 v[186:189], v149 offset:49152
	ds_read_b128 v[190:193], v149 offset:50176
	ds_read_b128 v[194:197], v149 offset:51200
	ds_read_b128 v[198:201], v149 offset:52224
	ds_read_b128 v[202:205], v149 offset:53248
	ds_read_b128 v[206:209], v149 offset:54272
	ds_read_b128 v[210:213], v149 offset:55296
	ds_read_b128 v[214:217], v149 offset:56320
	global_load_lds_dwordx4 v130, s[82:83]
	s_add_i32 m0, s33, 0x2000
	s_add_u32 s38, s38, 0x40080
	s_addc_u32 s39, s39, 0
	s_add_i32 s33, s34, s44
	global_load_lds_dwordx4 v134, s[82:83]
	s_mov_b32 m0, s33
	s_nop 0
	global_load_lds_dwordx4 v130, s[38:39]
	s_add_i32 m0, s33, 0x2000
	s_nop 0
	global_load_lds_dwordx4 v134, s[38:39]
	s_mov_b32 m0, s52
	s_nop 0
	global_load_lds_dwordx4 v128, s[84:85]
	s_mov_b32 m0, s53
	s_nop 0
	global_load_lds_dwordx4 v132, s[84:85]
	s_waitcnt vmcnt(8)
	s_waitcnt lgkmcnt(0)
	s_barrier
	s_setprio 1
	s_waitcnt lgkmcnt(0)
	v_mfma_f32_16x16x32_bf16 v[60:63], v[154:157], v[186:189], v[60:63]
	v_mfma_f32_16x16x32_bf16 v[52:55], v[162:165], v[186:189], v[52:55]
	v_mfma_f32_16x16x32_bf16 v[44:47], v[154:157], v[194:197], v[44:47]
	v_mfma_f32_16x16x32_bf16 v[36:39], v[162:165], v[194:197], v[36:39]
	v_mfma_f32_16x16x32_bf16 v[28:31], v[154:157], v[202:205], v[28:31]
	v_mfma_f32_16x16x32_bf16 v[20:23], v[162:165], v[202:205], v[20:23]
	v_mfma_f32_16x16x32_bf16 v[12:15], v[154:157], v[210:213], v[12:15]
	v_mfma_f32_16x16x32_bf16 v[4:7], v[162:165], v[210:213], v[4:7]
	v_mfma_f32_16x16x32_bf16 v[60:63], v[158:161], v[190:193], v[60:63]
	v_mfma_f32_16x16x32_bf16 v[52:55], v[166:169], v[190:193], v[52:55]
	v_mfma_f32_16x16x32_bf16 v[44:47], v[158:161], v[198:201], v[44:47]
	v_mfma_f32_16x16x32_bf16 v[36:39], v[166:169], v[198:201], v[36:39]
	v_mfma_f32_16x16x32_bf16 v[28:31], v[158:161], v[206:209], v[28:31]
	v_mfma_f32_16x16x32_bf16 v[20:23], v[166:169], v[206:209], v[20:23]
	v_mfma_f32_16x16x32_bf16 v[12:15], v[158:161], v[214:217], v[12:15]
	v_mfma_f32_16x16x32_bf16 v[4:7], v[166:169], v[214:217], v[4:7]
	s_setprio 0
	s_setprio 1
	v_mfma_f32_16x16x32_bf16 v[56:59], v[170:173], v[186:189], v[56:59]
	v_mfma_f32_16x16x32_bf16 v[48:51], v[178:181], v[186:189], v[48:51]
	v_mfma_f32_16x16x32_bf16 v[40:43], v[170:173], v[194:197], v[40:43]
	v_mfma_f32_16x16x32_bf16 v[32:35], v[178:181], v[194:197], v[32:35]
	v_mfma_f32_16x16x32_bf16 v[24:27], v[170:173], v[202:205], v[24:27]
	v_mfma_f32_16x16x32_bf16 v[16:19], v[178:181], v[202:205], v[16:19]
	v_mfma_f32_16x16x32_bf16 v[8:11], v[170:173], v[210:213], v[8:11]
	v_mfma_f32_16x16x32_bf16 v[0:3], v[178:181], v[210:213], v[0:3]
	v_mfma_f32_16x16x32_bf16 v[56:59], v[174:177], v[190:193], v[56:59]
	v_mfma_f32_16x16x32_bf16 v[48:51], v[182:185], v[190:193], v[48:51]
	v_mfma_f32_16x16x32_bf16 v[40:43], v[174:177], v[198:201], v[40:43]
	v_mfma_f32_16x16x32_bf16 v[32:35], v[182:185], v[198:201], v[32:35]
	v_mfma_f32_16x16x32_bf16 v[24:27], v[174:177], v[206:209], v[24:27]
	v_mfma_f32_16x16x32_bf16 v[16:19], v[182:185], v[206:209], v[16:19]
	v_mfma_f32_16x16x32_bf16 v[8:11], v[174:177], v[214:217], v[8:11]
	v_mfma_f32_16x16x32_bf16 v[0:3], v[182:185], v[214:217], v[0:3]
	s_setprio 0
	s_barrier
	s_add_i32 s62, s62, 2
	s_add_u32 s36, s36, 0x100
	s_addc_u32 s37, s37, 0
	s_add_u32 s60, s60, 0x100
	s_addc_u32 s61, s61, 0
	s_cmp_gt_u32 s62, 13
	s_cbranch_scc0 .LBB0_1342
	s_and_b64 vcc, exec, s[12:13]
	s_cbranch_vccz .LBB0_1345
	s_barrier
